# phase-10 gated epilogues: all gate/add tile loads issued up front (prologue/epilogue de-serialisation) on top of v92
# speedup vs baseline: 1.0018x; 1.0018x over previous
; __device__ __forceinline__ unsigned pk_bf16(float lo, float hi) { const f32x2 v = {lo, hi}; const bf16x2_t b = __builtin_convertvector(v, bf16x2_t); return __builtin_bit_cast(unsigned, b); }
; __device__ __forceinline__ float lo_bf(unsigned w) { return __uint_as_float(w << 16); }
; __device__ __forceinline__ float hi_bf(unsigned w) { return __uint_as_float(w & 0xffff0000u); }
;     __device__ __forceinline__ void operator()(const f32x4 (&acc)[2][2][4][2], const Unit& u, int wr, int wc, int fr, int fq) const {
;         const int row0 = u.pm * BM + wr * 64 + fr, col0 = u.pn * BM + wc * 32 + 8 * fq;
; #pragma unroll
;         for (int ai = 0; ai < 2; ++ai)
; #pragma unroll
;             for (int m = 0; m < 4; ++m) {
;                 const size_t off = (size_t)(row0 + ai * HALF + m * 16) * D + col0;
; #pragma unroll
;                 for (int bj = 0; bj < 2; ++bj) {
;                     const u32x4 gw = *(const u32x4*)(gate + off + bj * HALF);
;                     const f32x4 v0 = acc[ai][bj][m][0], v1 = acc[ai][bj][m][1];
;                     float r[8];
;                     r[0] = lo_bf(gw.x) * v0[0]; r[1] = hi_bf(gw.x) * v0[1]; r[2] = lo_bf(gw.y) * v0[2]; r[3] = hi_bf(gw.y) * v0[3];
;                     r[4] = lo_bf(gw.z) * v1[0]; r[5] = hi_bf(gw.z) * v1[1]; r[6] = lo_bf(gw.w) * v1[2]; r[7] = hi_bf(gw.w) * v1[3];
;                     if (ADD) {
;                         const u32x4 aw = *(const u32x4*)(add + off + bj * HALF);
;                         r[0] += lo_bf(aw.x); r[1] += hi_bf(aw.x); r[2] += lo_bf(aw.y); r[3] += hi_bf(aw.y);
;                         r[4] += lo_bf(aw.z); r[5] += hi_bf(aw.z); r[6] += lo_bf(aw.w); r[7] += hi_bf(aw.w);
;                     }
;                     u32x4 w; w.x = pk_bf16(r[0], r[1]); w.y = pk_bf16(r[2], r[3]); w.z = pk_bf16(r[4], r[5]); w.w = pk_bf16(r[6], r[7]);
;                     *(u32x4*)(out + off + bj * HALF) = w;
;                 }
;                 asm volatile("" ::: "memory");
;             }
;     }
.LBB0_891:
	s_lshl_b32 s30, s30, 8
	v_mbcnt_lo_u32_b32 v146, -1, 0
	v_mbcnt_hi_u32_b32 v146, -1, v146
	s_add_i32 s30, s30, s60
	v_and_or_b32 v150, v146, 15, s30
	s_lshl_b32 s30, s33, 8
	v_ashrrev_i32_e32 v146, 1, v146
	s_or_b32 s30, s30, s61
	v_and_b32_e32 v146, -8, v146
	v_add_u32_e32 v148, s30, v146
	v_ashrrev_i32_e32 v151, 31, v150
	v_ashrrev_i32_e32 v149, 31, v148
	v_lshlrev_b64 v[146:147], 10, v[150:151]
	v_lshl_add_u64 v[146:147], v[146:147], 0, v[148:149]
	v_lshlrev_b64 v[146:147], 1, v[146:147]
	v_lshl_add_u64 v[172:173], s[24:25], 0, v[146:147]
	v_add_u32_e32 v244, 0x8000, v146
	v_add_u32_e32 v245, 0x10000, v146
	v_add_u32_e32 v246, 0x18000, v146
	v_add_u32_e32 v247, 0x40000, v146
	v_add_u32_e32 v248, 0x48000, v146
	v_add_u32_e32 v148, 0x50000, v146
	v_add_u32_e32 v149, 0x58000, v146
	global_load_dwordx4 v[156:159], v146, s[24:25]
	global_load_dwordx4 v[160:163], v146, s[18:19]
	global_load_dwordx4 v[164:167], v146, s[24:25] offset:256
	global_load_dwordx4 v[168:171], v146, s[18:19] offset:256
	global_load_dwordx4 v[172:175], v244, s[24:25]
	global_load_dwordx4 v[176:179], v244, s[18:19]
	global_load_dwordx4 v[180:183], v244, s[24:25] offset:256
	global_load_dwordx4 v[184:187], v244, s[18:19] offset:256
	global_load_dwordx4 v[188:191], v245, s[24:25]
	global_load_dwordx4 v[192:195], v245, s[18:19]
	global_load_dwordx4 v[196:199], v245, s[24:25] offset:256
	global_load_dwordx4 v[200:203], v245, s[18:19] offset:256
	global_load_dwordx4 v[204:207], v246, s[24:25]
	global_load_dwordx4 v[208:211], v246, s[18:19]
	global_load_dwordx4 v[212:215], v246, s[24:25] offset:256
	global_load_dwordx4 v[216:219], v246, s[18:19] offset:256
	s_waitcnt vmcnt(12)
	v_lshlrev_b32_e32 v220, 16, v156
	v_and_b32_e32 v221, 0xffff0000, v156
	v_lshlrev_b32_e32 v228, 16, v160
	v_and_b32_e32 v229, 0xffff0000, v160
	v_lshlrev_b32_e32 v222, 16, v157
	v_and_b32_e32 v223, 0xffff0000, v157
	v_lshlrev_b32_e32 v230, 16, v161
	v_and_b32_e32 v231, 0xffff0000, v161
	v_lshlrev_b32_e32 v224, 16, v158
	v_and_b32_e32 v225, 0xffff0000, v158
	v_lshlrev_b32_e32 v232, 16, v162
	v_and_b32_e32 v233, 0xffff0000, v162
	v_lshlrev_b32_e32 v226, 16, v159
	v_and_b32_e32 v227, 0xffff0000, v159
	v_lshlrev_b32_e32 v234, 16, v163
	v_and_b32_e32 v235, 0xffff0000, v163
	v_pk_fma_f32 v[124:125], v[124:125], v[220:221], v[228:229]
	v_pk_fma_f32 v[126:127], v[126:127], v[222:223], v[230:231]
	v_pk_fma_f32 v[120:121], v[120:121], v[224:225], v[232:233]
	v_pk_fma_f32 v[122:123], v[122:123], v[226:227], v[234:235]
	s_nop 0
	v_cvt_pk_bf16_f32 v236, v124, v125
	v_cvt_pk_bf16_f32 v237, v126, v127
	v_cvt_pk_bf16_f32 v238, v120, v121
	v_cvt_pk_bf16_f32 v239, v122, v123
	v_lshlrev_b32_e32 v220, 16, v164
	v_and_b32_e32 v221, 0xffff0000, v164
	v_lshlrev_b32_e32 v228, 16, v168
	v_and_b32_e32 v229, 0xffff0000, v168
	v_lshlrev_b32_e32 v222, 16, v165
	v_and_b32_e32 v223, 0xffff0000, v165
	v_lshlrev_b32_e32 v230, 16, v169
	v_and_b32_e32 v231, 0xffff0000, v169
	v_lshlrev_b32_e32 v224, 16, v166
	v_and_b32_e32 v225, 0xffff0000, v166
	v_lshlrev_b32_e32 v232, 16, v170
	v_and_b32_e32 v233, 0xffff0000, v170
	v_lshlrev_b32_e32 v226, 16, v167
	v_and_b32_e32 v227, 0xffff0000, v167
	v_lshlrev_b32_e32 v234, 16, v171
	v_and_b32_e32 v235, 0xffff0000, v171
	v_pk_fma_f32 v[116:117], v[116:117], v[220:221], v[228:229]
	v_pk_fma_f32 v[118:119], v[118:119], v[222:223], v[230:231]
	v_pk_fma_f32 v[112:113], v[112:113], v[224:225], v[232:233]
	v_pk_fma_f32 v[114:115], v[114:115], v[226:227], v[234:235]
	v_cvt_pk_bf16_f32 v240, v116, v117
	v_cvt_pk_bf16_f32 v241, v118, v119
	v_cvt_pk_bf16_f32 v242, v112, v113
	v_cvt_pk_bf16_f32 v243, v114, v115
	global_store_dwordx4 v146, v[236:239], s[24:25]
	global_store_dwordx4 v146, v[240:243], s[24:25] offset:256
	global_load_dwordx4 v[156:159], v247, s[24:25]
	global_load_dwordx4 v[160:163], v247, s[18:19]
	global_load_dwordx4 v[164:167], v247, s[24:25] offset:256
	global_load_dwordx4 v[168:171], v247, s[18:19] offset:256
	s_waitcnt vmcnt(14)
	v_lshlrev_b32_e32 v220, 16, v172
	v_and_b32_e32 v221, 0xffff0000, v172
	v_lshlrev_b32_e32 v228, 16, v176
	v_and_b32_e32 v229, 0xffff0000, v176
	v_lshlrev_b32_e32 v222, 16, v173
	v_and_b32_e32 v223, 0xffff0000, v173
	v_lshlrev_b32_e32 v230, 16, v177
	v_and_b32_e32 v231, 0xffff0000, v177
	v_lshlrev_b32_e32 v224, 16, v174
	v_and_b32_e32 v225, 0xffff0000, v174
	v_lshlrev_b32_e32 v232, 16, v178
	v_and_b32_e32 v233, 0xffff0000, v178
	v_lshlrev_b32_e32 v226, 16, v175
	v_and_b32_e32 v227, 0xffff0000, v175
	v_lshlrev_b32_e32 v234, 16, v179
	v_and_b32_e32 v235, 0xffff0000, v179
	v_pk_fma_f32 v[108:109], v[108:109], v[220:221], v[228:229]
	v_pk_fma_f32 v[110:111], v[110:111], v[222:223], v[230:231]
	v_pk_fma_f32 v[104:105], v[104:105], v[224:225], v[232:233]
	v_pk_fma_f32 v[106:107], v[106:107], v[226:227], v[234:235]
	s_nop 0
	v_cvt_pk_bf16_f32 v236, v108, v109
	v_cvt_pk_bf16_f32 v237, v110, v111
	v_cvt_pk_bf16_f32 v238, v104, v105
	v_cvt_pk_bf16_f32 v239, v106, v107
	v_lshlrev_b32_e32 v220, 16, v180
	v_and_b32_e32 v221, 0xffff0000, v180
	v_lshlrev_b32_e32 v228, 16, v184
	v_and_b32_e32 v229, 0xffff0000, v184
	v_lshlrev_b32_e32 v222, 16, v181
	v_and_b32_e32 v223, 0xffff0000, v181
	v_lshlrev_b32_e32 v230, 16, v185
	v_and_b32_e32 v231, 0xffff0000, v185
	v_lshlrev_b32_e32 v224, 16, v182
	v_and_b32_e32 v225, 0xffff0000, v182
	v_lshlrev_b32_e32 v232, 16, v186
	v_and_b32_e32 v233, 0xffff0000, v186
	v_lshlrev_b32_e32 v226, 16, v183
	v_and_b32_e32 v227, 0xffff0000, v183
	v_lshlrev_b32_e32 v234, 16, v187
	v_and_b32_e32 v235, 0xffff0000, v187
	v_pk_fma_f32 v[100:101], v[100:101], v[220:221], v[228:229]
	v_pk_fma_f32 v[102:103], v[102:103], v[222:223], v[230:231]
	v_pk_fma_f32 v[96:97], v[96:97], v[224:225], v[232:233]
	v_pk_fma_f32 v[98:99], v[98:99], v[226:227], v[234:235]
	v_cvt_pk_bf16_f32 v240, v100, v101
	v_cvt_pk_bf16_f32 v241, v102, v103
	v_cvt_pk_bf16_f32 v242, v96, v97
	v_cvt_pk_bf16_f32 v243, v98, v99
	global_store_dwordx4 v244, v[236:239], s[24:25]
	global_store_dwordx4 v244, v[240:243], s[24:25] offset:256
	global_load_dwordx4 v[172:175], v248, s[24:25]
	global_load_dwordx4 v[176:179], v248, s[18:19]
	global_load_dwordx4 v[180:183], v248, s[24:25] offset:256
	global_load_dwordx4 v[184:187], v248, s[18:19] offset:256
	s_waitcnt vmcnt(16)
; __device__ __forceinline__ unsigned pk_bf16(float lo, float hi) { const f32x2 v = {lo, hi}; const bf16x2_t b = __builtin_convertvector(v, bf16x2_t); return __builtin_bit_cast(unsigned, b); }
; __device__ __forceinline__ float lo_bf(unsigned w) { return __uint_as_float(w << 16); }
; __device__ __forceinline__ float hi_bf(unsigned w) { return __uint_as_float(w & 0xffff0000u); }
;     __device__ __forceinline__ void operator()(const f32x4 (&acc)[2][2][4][2], const Unit& u, int wr, int wc, int fr, int fq) const {
;     ...
;                 for (int bj = 0; bj < 2; ++bj) {
;                     const u32x4 gw = *(const u32x4*)(gate + off + bj * HALF);
;                     const f32x4 v0 = acc[ai][bj][m][0], v1 = acc[ai][bj][m][1];
;                     float r[8];
;                     r[0] = lo_bf(gw.x) * v0[0]; r[1] = hi_bf(gw.x) * v0[1]; r[2] = lo_bf(gw.y) * v0[2]; r[3] = hi_bf(gw.y) * v0[3];
;                     r[4] = lo_bf(gw.z) * v1[0]; r[5] = hi_bf(gw.z) * v1[1]; r[6] = lo_bf(gw.w) * v1[2]; r[7] = hi_bf(gw.w) * v1[3];
;                     if (ADD) {
;                         const u32x4 aw = *(const u32x4*)(add + off + bj * HALF);
;                         r[0] += lo_bf(aw.x); r[1] += hi_bf(aw.x); r[2] += lo_bf(aw.y); r[3] += hi_bf(aw.y);
;                         r[4] += lo_bf(aw.z); r[5] += hi_bf(aw.z); r[6] += lo_bf(aw.w); r[7] += hi_bf(aw.w);
;                     }
;                     u32x4 w; w.x = pk_bf16(r[0], r[1]); w.y = pk_bf16(r[2], r[3]); w.z = pk_bf16(r[4], r[5]); w.w = pk_bf16(r[6], r[7]);
;                     *(u32x4*)(out + off + bj * HALF) = w;
;                 }
;                 asm volatile("" ::: "memory");
	v_lshlrev_b32_e32 v220, 16, v188
	v_and_b32_e32 v221, 0xffff0000, v188
	v_lshlrev_b32_e32 v228, 16, v192
	v_and_b32_e32 v229, 0xffff0000, v192
	v_lshlrev_b32_e32 v222, 16, v189
	v_and_b32_e32 v223, 0xffff0000, v189
	v_lshlrev_b32_e32 v230, 16, v193
	v_and_b32_e32 v231, 0xffff0000, v193
	v_lshlrev_b32_e32 v224, 16, v190
	v_and_b32_e32 v225, 0xffff0000, v190
	v_lshlrev_b32_e32 v232, 16, v194
	v_and_b32_e32 v233, 0xffff0000, v194
	v_lshlrev_b32_e32 v226, 16, v191
	v_and_b32_e32 v227, 0xffff0000, v191
	v_lshlrev_b32_e32 v234, 16, v195
	v_and_b32_e32 v235, 0xffff0000, v195
	v_pk_fma_f32 v[92:93], v[92:93], v[220:221], v[228:229]
	v_pk_fma_f32 v[94:95], v[94:95], v[222:223], v[230:231]
	v_pk_fma_f32 v[88:89], v[88:89], v[224:225], v[232:233]
	v_pk_fma_f32 v[90:91], v[90:91], v[226:227], v[234:235]
	s_nop 0
	v_cvt_pk_bf16_f32 v236, v92, v93
	v_cvt_pk_bf16_f32 v237, v94, v95
	v_cvt_pk_bf16_f32 v238, v88, v89
	v_cvt_pk_bf16_f32 v239, v90, v91
	v_lshlrev_b32_e32 v220, 16, v196
	v_and_b32_e32 v221, 0xffff0000, v196
	v_lshlrev_b32_e32 v228, 16, v200
	v_and_b32_e32 v229, 0xffff0000, v200
	v_lshlrev_b32_e32 v222, 16, v197
	v_and_b32_e32 v223, 0xffff0000, v197
	v_lshlrev_b32_e32 v230, 16, v201
	v_and_b32_e32 v231, 0xffff0000, v201
	v_lshlrev_b32_e32 v224, 16, v198
	v_and_b32_e32 v225, 0xffff0000, v198
	v_lshlrev_b32_e32 v232, 16, v202
	v_and_b32_e32 v233, 0xffff0000, v202
	v_lshlrev_b32_e32 v226, 16, v199
	v_and_b32_e32 v227, 0xffff0000, v199
	v_lshlrev_b32_e32 v234, 16, v203
	v_and_b32_e32 v235, 0xffff0000, v203
	v_pk_fma_f32 v[84:85], v[84:85], v[220:221], v[228:229]
	v_pk_fma_f32 v[86:87], v[86:87], v[222:223], v[230:231]
	v_pk_fma_f32 v[80:81], v[80:81], v[224:225], v[232:233]
	v_pk_fma_f32 v[82:83], v[82:83], v[226:227], v[234:235]
	v_cvt_pk_bf16_f32 v240, v84, v85
	v_cvt_pk_bf16_f32 v241, v86, v87
	v_cvt_pk_bf16_f32 v242, v80, v81
	v_cvt_pk_bf16_f32 v243, v82, v83
	global_store_dwordx4 v245, v[236:239], s[24:25]
	global_store_dwordx4 v245, v[240:243], s[24:25] offset:256
	global_load_dwordx4 v[188:191], v148, s[24:25]
	global_load_dwordx4 v[192:195], v148, s[18:19]
	global_load_dwordx4 v[196:199], v148, s[24:25] offset:256
	global_load_dwordx4 v[200:203], v148, s[18:19] offset:256
	s_waitcnt vmcnt(18)
	v_lshlrev_b32_e32 v220, 16, v204
	v_and_b32_e32 v221, 0xffff0000, v204
	v_lshlrev_b32_e32 v228, 16, v208
	v_and_b32_e32 v229, 0xffff0000, v208
	v_lshlrev_b32_e32 v222, 16, v205
	v_and_b32_e32 v223, 0xffff0000, v205
	v_lshlrev_b32_e32 v230, 16, v209
	v_and_b32_e32 v231, 0xffff0000, v209
	v_lshlrev_b32_e32 v224, 16, v206
	v_and_b32_e32 v225, 0xffff0000, v206
	v_lshlrev_b32_e32 v232, 16, v210
	v_and_b32_e32 v233, 0xffff0000, v210
	v_lshlrev_b32_e32 v226, 16, v207
	v_and_b32_e32 v227, 0xffff0000, v207
	v_lshlrev_b32_e32 v234, 16, v211
	v_and_b32_e32 v235, 0xffff0000, v211
	v_pk_fma_f32 v[76:77], v[76:77], v[220:221], v[228:229]
	v_pk_fma_f32 v[78:79], v[78:79], v[222:223], v[230:231]
	v_pk_fma_f32 v[72:73], v[72:73], v[224:225], v[232:233]
	v_pk_fma_f32 v[74:75], v[74:75], v[226:227], v[234:235]
	s_nop 0
	v_cvt_pk_bf16_f32 v236, v76, v77
	v_cvt_pk_bf16_f32 v237, v78, v79
	v_cvt_pk_bf16_f32 v238, v72, v73
	v_cvt_pk_bf16_f32 v239, v74, v75
	v_lshlrev_b32_e32 v220, 16, v212
	v_and_b32_e32 v221, 0xffff0000, v212
	v_lshlrev_b32_e32 v228, 16, v216
	v_and_b32_e32 v229, 0xffff0000, v216
	v_lshlrev_b32_e32 v222, 16, v213
	v_and_b32_e32 v223, 0xffff0000, v213
	v_lshlrev_b32_e32 v230, 16, v217
	v_and_b32_e32 v231, 0xffff0000, v217
	v_lshlrev_b32_e32 v224, 16, v214
	v_and_b32_e32 v225, 0xffff0000, v214
	v_lshlrev_b32_e32 v232, 16, v218
	v_and_b32_e32 v233, 0xffff0000, v218
	v_lshlrev_b32_e32 v226, 16, v215
	v_and_b32_e32 v227, 0xffff0000, v215
	v_lshlrev_b32_e32 v234, 16, v219
	v_and_b32_e32 v235, 0xffff0000, v219
	v_pk_fma_f32 v[68:69], v[68:69], v[220:221], v[228:229]
	v_pk_fma_f32 v[70:71], v[70:71], v[222:223], v[230:231]
	v_pk_fma_f32 v[64:65], v[64:65], v[224:225], v[232:233]
	v_pk_fma_f32 v[66:67], v[66:67], v[226:227], v[234:235]
	v_cvt_pk_bf16_f32 v240, v68, v69
	v_cvt_pk_bf16_f32 v241, v70, v71
	v_cvt_pk_bf16_f32 v242, v64, v65
	v_cvt_pk_bf16_f32 v243, v66, v67
	global_store_dwordx4 v246, v[236:239], s[24:25]
	global_store_dwordx4 v246, v[240:243], s[24:25] offset:256
	global_load_dwordx4 v[204:207], v149, s[24:25]
	global_load_dwordx4 v[208:211], v149, s[18:19]
	global_load_dwordx4 v[212:215], v149, s[24:25] offset:256
	global_load_dwordx4 v[216:219], v149, s[18:19] offset:256
	s_waitcnt vmcnt(18)
	v_lshlrev_b32_e32 v220, 16, v156
	v_and_b32_e32 v221, 0xffff0000, v156
	v_lshlrev_b32_e32 v228, 16, v160
	v_and_b32_e32 v229, 0xffff0000, v160
	v_lshlrev_b32_e32 v222, 16, v157
	v_and_b32_e32 v223, 0xffff0000, v157
	v_lshlrev_b32_e32 v230, 16, v161
	v_and_b32_e32 v231, 0xffff0000, v161
	v_lshlrev_b32_e32 v224, 16, v158
	v_and_b32_e32 v225, 0xffff0000, v158
	v_lshlrev_b32_e32 v232, 16, v162
	v_and_b32_e32 v233, 0xffff0000, v162
	v_lshlrev_b32_e32 v226, 16, v159
	v_and_b32_e32 v227, 0xffff0000, v159
	v_lshlrev_b32_e32 v234, 16, v163
	v_and_b32_e32 v235, 0xffff0000, v163
	v_pk_fma_f32 v[60:61], v[60:61], v[220:221], v[228:229]
	v_pk_fma_f32 v[62:63], v[62:63], v[222:223], v[230:231]
	v_pk_fma_f32 v[56:57], v[56:57], v[224:225], v[232:233]
	v_pk_fma_f32 v[58:59], v[58:59], v[226:227], v[234:235]
	s_nop 0
	v_cvt_pk_bf16_f32 v236, v60, v61
	v_cvt_pk_bf16_f32 v237, v62, v63
	v_cvt_pk_bf16_f32 v238, v56, v57
	v_cvt_pk_bf16_f32 v239, v58, v59
	v_lshlrev_b32_e32 v220, 16, v164
	v_and_b32_e32 v221, 0xffff0000, v164
	v_lshlrev_b32_e32 v228, 16, v168
	v_and_b32_e32 v229, 0xffff0000, v168
	v_lshlrev_b32_e32 v222, 16, v165
	v_and_b32_e32 v223, 0xffff0000, v165
	v_lshlrev_b32_e32 v230, 16, v169
	v_and_b32_e32 v231, 0xffff0000, v169
	v_lshlrev_b32_e32 v224, 16, v166
	v_and_b32_e32 v225, 0xffff0000, v166
	v_lshlrev_b32_e32 v232, 16, v170
	v_and_b32_e32 v233, 0xffff0000, v170
	v_lshlrev_b32_e32 v226, 16, v167
	v_and_b32_e32 v227, 0xffff0000, v167
	v_lshlrev_b32_e32 v234, 16, v171
	v_and_b32_e32 v235, 0xffff0000, v171
	v_pk_fma_f32 v[52:53], v[52:53], v[220:221], v[228:229]
	v_pk_fma_f32 v[54:55], v[54:55], v[222:223], v[230:231]
	v_pk_fma_f32 v[48:49], v[48:49], v[224:225], v[232:233]
	v_pk_fma_f32 v[50:51], v[50:51], v[226:227], v[234:235]
	v_cvt_pk_bf16_f32 v240, v52, v53
	v_cvt_pk_bf16_f32 v241, v54, v55
	v_cvt_pk_bf16_f32 v242, v48, v49
	v_cvt_pk_bf16_f32 v243, v50, v51
	global_store_dwordx4 v247, v[236:239], s[24:25]
	global_store_dwordx4 v247, v[240:243], s[24:25] offset:256
	s_waitcnt vmcnt(14)
; __device__ __forceinline__ unsigned pk_bf16(float lo, float hi) { const f32x2 v = {lo, hi}; const bf16x2_t b = __builtin_convertvector(v, bf16x2_t); return __builtin_bit_cast(unsigned, b); }
; __device__ __forceinline__ float lo_bf(unsigned w) { return __uint_as_float(w << 16); }
; __device__ __forceinline__ float hi_bf(unsigned w) { return __uint_as_float(w & 0xffff0000u); }
; template <class Epi, bool SP2 = false>
; __device__ __forceinline__ void gemm_phase(LAS unsigned char* lds, const Gemm g, const StaticOrder& S, const Epi& E) {
;     ...
;         if (!has_next) break;
; #pragma unroll
;         for (int a = 0; a < 2; ++a)
; #pragma unroll
;             for (int b = 0; b < 2; ++b)
; #pragma unroll
;                 for (int m = 0; m < 4; ++m)
; #pragma unroll
;                     for (int n = 0; n < 2; ++n) acc[a][b][m][n] = (f32x4){0.f, 0.f, 0.f, 0.f};
;         cur = nxt; cA = nA; cB = nB; ++ui;
;     __device__ __forceinline__ void operator()(const f32x4 (&acc)[2][2][4][2], const Unit& u, int wr, int wc, int fr, int fq) const {
;     ...
;                 for (int bj = 0; bj < 2; ++bj) {
;                     const u32x4 gw = *(const u32x4*)(gate + off + bj * HALF);
;                     const f32x4 v0 = acc[ai][bj][m][0], v1 = acc[ai][bj][m][1];
;                     float r[8];
;                     r[0] = lo_bf(gw.x) * v0[0]; r[1] = hi_bf(gw.x) * v0[1]; r[2] = lo_bf(gw.y) * v0[2]; r[3] = hi_bf(gw.y) * v0[3];
;                     r[4] = lo_bf(gw.z) * v1[0]; r[5] = hi_bf(gw.z) * v1[1]; r[6] = lo_bf(gw.w) * v1[2]; r[7] = hi_bf(gw.w) * v1[3];
;                     if (ADD) {
;                         const u32x4 aw = *(const u32x4*)(add + off + bj * HALF);
;                         r[0] += lo_bf(aw.x); r[1] += hi_bf(aw.x); r[2] += lo_bf(aw.y); r[3] += hi_bf(aw.y);
;                         r[4] += lo_bf(aw.z); r[5] += hi_bf(aw.z); r[6] += lo_bf(aw.w); r[7] += hi_bf(aw.w);
;                     }
;                     u32x4 w; w.x = pk_bf16(r[0], r[1]); w.y = pk_bf16(r[2], r[3]); w.z = pk_bf16(r[4], r[5]); w.w = pk_bf16(r[6], r[7]);
;                     *(u32x4*)(out + off + bj * HALF) = w;
;                 }
;                 asm volatile("" ::: "memory");
;             }
;     }
	v_lshlrev_b32_e32 v220, 16, v172
	v_and_b32_e32 v221, 0xffff0000, v172
	v_lshlrev_b32_e32 v228, 16, v176
	v_and_b32_e32 v229, 0xffff0000, v176
	v_lshlrev_b32_e32 v222, 16, v173
	v_and_b32_e32 v223, 0xffff0000, v173
	v_lshlrev_b32_e32 v230, 16, v177
	v_and_b32_e32 v231, 0xffff0000, v177
	v_lshlrev_b32_e32 v224, 16, v174
	v_and_b32_e32 v225, 0xffff0000, v174
	v_lshlrev_b32_e32 v232, 16, v178
	v_and_b32_e32 v233, 0xffff0000, v178
	v_lshlrev_b32_e32 v226, 16, v175
	v_and_b32_e32 v227, 0xffff0000, v175
	v_lshlrev_b32_e32 v234, 16, v179
	v_and_b32_e32 v235, 0xffff0000, v179
	v_pk_fma_f32 v[44:45], v[44:45], v[220:221], v[228:229]
	v_pk_fma_f32 v[46:47], v[46:47], v[222:223], v[230:231]
	v_pk_fma_f32 v[40:41], v[40:41], v[224:225], v[232:233]
	v_pk_fma_f32 v[42:43], v[42:43], v[226:227], v[234:235]
	s_nop 0
	v_cvt_pk_bf16_f32 v236, v44, v45
	v_cvt_pk_bf16_f32 v237, v46, v47
	v_cvt_pk_bf16_f32 v238, v40, v41
	v_cvt_pk_bf16_f32 v239, v42, v43
	v_lshlrev_b32_e32 v220, 16, v180
	v_and_b32_e32 v221, 0xffff0000, v180
	v_lshlrev_b32_e32 v228, 16, v184
	v_and_b32_e32 v229, 0xffff0000, v184
	v_lshlrev_b32_e32 v222, 16, v181
	v_and_b32_e32 v223, 0xffff0000, v181
	v_lshlrev_b32_e32 v230, 16, v185
	v_and_b32_e32 v231, 0xffff0000, v185
	v_lshlrev_b32_e32 v224, 16, v182
	v_and_b32_e32 v225, 0xffff0000, v182
	v_lshlrev_b32_e32 v232, 16, v186
	v_and_b32_e32 v233, 0xffff0000, v186
	v_lshlrev_b32_e32 v226, 16, v183
	v_and_b32_e32 v227, 0xffff0000, v183
	v_lshlrev_b32_e32 v234, 16, v187
	v_and_b32_e32 v235, 0xffff0000, v187
	v_pk_fma_f32 v[36:37], v[36:37], v[220:221], v[228:229]
	v_pk_fma_f32 v[38:39], v[38:39], v[222:223], v[230:231]
	v_pk_fma_f32 v[32:33], v[32:33], v[224:225], v[232:233]
	v_pk_fma_f32 v[34:35], v[34:35], v[226:227], v[234:235]
	v_cvt_pk_bf16_f32 v240, v36, v37
	v_cvt_pk_bf16_f32 v241, v38, v39
	v_cvt_pk_bf16_f32 v242, v32, v33
	v_cvt_pk_bf16_f32 v243, v34, v35
	global_store_dwordx4 v248, v[236:239], s[24:25]
	global_store_dwordx4 v248, v[240:243], s[24:25] offset:256
	s_waitcnt vmcnt(10)
	v_lshlrev_b32_e32 v220, 16, v188
	v_and_b32_e32 v221, 0xffff0000, v188
	v_lshlrev_b32_e32 v228, 16, v192
	v_and_b32_e32 v229, 0xffff0000, v192
	v_lshlrev_b32_e32 v222, 16, v189
	v_and_b32_e32 v223, 0xffff0000, v189
	v_lshlrev_b32_e32 v230, 16, v193
	v_and_b32_e32 v231, 0xffff0000, v193
	v_lshlrev_b32_e32 v224, 16, v190
	v_and_b32_e32 v225, 0xffff0000, v190
	v_lshlrev_b32_e32 v232, 16, v194
	v_and_b32_e32 v233, 0xffff0000, v194
	v_lshlrev_b32_e32 v226, 16, v191
	v_and_b32_e32 v227, 0xffff0000, v191
	v_lshlrev_b32_e32 v234, 16, v195
	v_and_b32_e32 v235, 0xffff0000, v195
	v_pk_fma_f32 v[28:29], v[28:29], v[220:221], v[228:229]
	v_pk_fma_f32 v[30:31], v[30:31], v[222:223], v[230:231]
	v_pk_fma_f32 v[24:25], v[24:25], v[224:225], v[232:233]
	v_pk_fma_f32 v[26:27], v[26:27], v[226:227], v[234:235]
	s_nop 0
	v_cvt_pk_bf16_f32 v236, v28, v29
	v_cvt_pk_bf16_f32 v237, v30, v31
	v_cvt_pk_bf16_f32 v238, v24, v25
	v_cvt_pk_bf16_f32 v239, v26, v27
	v_lshlrev_b32_e32 v220, 16, v196
	v_and_b32_e32 v221, 0xffff0000, v196
	v_lshlrev_b32_e32 v228, 16, v200
	v_and_b32_e32 v229, 0xffff0000, v200
	v_lshlrev_b32_e32 v222, 16, v197
	v_and_b32_e32 v223, 0xffff0000, v197
	v_lshlrev_b32_e32 v230, 16, v201
	v_and_b32_e32 v231, 0xffff0000, v201
	v_lshlrev_b32_e32 v224, 16, v198
	v_and_b32_e32 v225, 0xffff0000, v198
	v_lshlrev_b32_e32 v232, 16, v202
	v_and_b32_e32 v233, 0xffff0000, v202
	v_lshlrev_b32_e32 v226, 16, v199
	v_and_b32_e32 v227, 0xffff0000, v199
	v_lshlrev_b32_e32 v234, 16, v203
	v_and_b32_e32 v235, 0xffff0000, v203
	v_pk_fma_f32 v[20:21], v[20:21], v[220:221], v[228:229]
	v_pk_fma_f32 v[22:23], v[22:23], v[222:223], v[230:231]
	v_pk_fma_f32 v[16:17], v[16:17], v[224:225], v[232:233]
	v_pk_fma_f32 v[18:19], v[18:19], v[226:227], v[234:235]
	v_cvt_pk_bf16_f32 v240, v20, v21
	v_cvt_pk_bf16_f32 v241, v22, v23
	v_cvt_pk_bf16_f32 v242, v16, v17
	v_cvt_pk_bf16_f32 v243, v18, v19
	global_store_dwordx4 v148, v[236:239], s[24:25]
	global_store_dwordx4 v148, v[240:243], s[24:25] offset:256
	s_waitcnt vmcnt(6)
	v_lshlrev_b32_e32 v220, 16, v204
	v_and_b32_e32 v221, 0xffff0000, v204
	v_lshlrev_b32_e32 v228, 16, v208
	v_and_b32_e32 v229, 0xffff0000, v208
	v_lshlrev_b32_e32 v222, 16, v205
	v_and_b32_e32 v223, 0xffff0000, v205
	v_lshlrev_b32_e32 v230, 16, v209
	v_and_b32_e32 v231, 0xffff0000, v209
	v_lshlrev_b32_e32 v224, 16, v206
	v_and_b32_e32 v225, 0xffff0000, v206
	v_lshlrev_b32_e32 v232, 16, v210
	v_and_b32_e32 v233, 0xffff0000, v210
	v_lshlrev_b32_e32 v226, 16, v207
	v_and_b32_e32 v227, 0xffff0000, v207
	v_lshlrev_b32_e32 v234, 16, v211
	v_and_b32_e32 v235, 0xffff0000, v211
	v_pk_fma_f32 v[12:13], v[12:13], v[220:221], v[228:229]
	v_pk_fma_f32 v[14:15], v[14:15], v[222:223], v[230:231]
	v_pk_fma_f32 v[8:9], v[8:9], v[224:225], v[232:233]
	v_pk_fma_f32 v[10:11], v[10:11], v[226:227], v[234:235]
	s_nop 0
	v_cvt_pk_bf16_f32 v236, v12, v13
	v_cvt_pk_bf16_f32 v237, v14, v15
	v_cvt_pk_bf16_f32 v238, v8, v9
	v_cvt_pk_bf16_f32 v239, v10, v11
	v_lshlrev_b32_e32 v220, 16, v212
	v_and_b32_e32 v221, 0xffff0000, v212
	v_lshlrev_b32_e32 v228, 16, v216
	v_and_b32_e32 v229, 0xffff0000, v216
	v_lshlrev_b32_e32 v222, 16, v213
	v_and_b32_e32 v223, 0xffff0000, v213
	v_lshlrev_b32_e32 v230, 16, v217
	v_and_b32_e32 v231, 0xffff0000, v217
	v_lshlrev_b32_e32 v224, 16, v214
	v_and_b32_e32 v225, 0xffff0000, v214
	v_lshlrev_b32_e32 v232, 16, v218
	v_and_b32_e32 v233, 0xffff0000, v218
	v_lshlrev_b32_e32 v226, 16, v215
	v_and_b32_e32 v227, 0xffff0000, v215
	v_lshlrev_b32_e32 v234, 16, v219
	v_and_b32_e32 v235, 0xffff0000, v219
	v_pk_fma_f32 v[4:5], v[4:5], v[220:221], v[228:229]
	v_pk_fma_f32 v[6:7], v[6:7], v[222:223], v[230:231]
	v_pk_fma_f32 v[0:1], v[0:1], v[224:225], v[232:233]
	v_pk_fma_f32 v[2:3], v[2:3], v[226:227], v[234:235]
	v_cvt_pk_bf16_f32 v240, v4, v5
	v_cvt_pk_bf16_f32 v241, v6, v7
	v_cvt_pk_bf16_f32 v242, v0, v1
	v_cvt_pk_bf16_f32 v243, v2, v3
	global_store_dwordx4 v149, v[236:239], s[24:25]
	global_store_dwordx4 v149, v[240:243], s[24:25] offset:256
	s_andn2_b64 vcc, exec, s[0:1]
	s_mov_b64 s[0:1], -1
	s_cbranch_vccnz .LBB0_884
	s_andn2_b64 vcc, exec, s[8:9]
	s_cbranch_vccnz .LBB0_883
	s_barrier
	s_branch .LBB0_883
